# P5 skinny tile K loop rewritten: operands streamed as whole 1-KiB image blocks by LDS-DMA into the wave's own ring slice (double-buffered 32-k chunks), fragments by ds_read_b128; same MFMA order
# speedup vs baseline: 1.0023x; 1.0023x over previous
; __host__ __device__ __forceinline__ size_t img_off(int row, int col, int nkt) { return ((size_t)((row >> 7) * nkt + (col >> 6)) << 14) + (size_t)lds_byte(row & 127, col & 63); }
; __host__ __device__ __forceinline__ size_t img_off_b(int row, int col, int nkt) { return img_off((row & ~31) | invperm32(row & 31), col, nkt); }
; template <int K, int MODE>
; __device__ __forceinline__ void skinny_tile(Frame& F, const Args& A, const bf16* Am  , const bf16* Bt  ) {
;     ...
;     constexpr int KW = K / 8, NK = KW / 16;
;     const char* ab = (const char*)Am; const char* bb = (const char*)Bt; const int arow = MP + r0 + il, brow = c0 + il, kc0 = w * KW + 8 * hi;
;     f32x16 acc0, acc1;
; #pragma unroll
;     for (int q = 0; q < 16; ++q) { acc0[q] = 0.f; acc1[q] = 0.f; }
;     constexpr int CH = (NK % 8 == 0) ? 8 : 11;
;     static_assert(NK % CH == 0, "skinny_tile: K slice");
; #pragma unroll 1
;     for (int k0 = 0; k0 < NK; k0 += CH) {
;         bf16x8 bf[CH], a0[CH], a1[CH];
; #pragma unroll
;         for (int c = 0; c < CH; ++c) { const int kc = kc0 + 16 * (k0 + c); bf[c] = *(const bf16x8*)(bb + pg8::img_off_b(brow, kc, K / 64)); a0[c] = *(const bf16x8*)(ab + pg8::img_off(arow, kc, K / 64)); a1[c] = *(const bf16x8*)(ab + pg8::img_off(arow + 32, kc, K / 64)); }
; #pragma unroll
;         for (int c = 0; c < CH; ++c) { acc0 = __builtin_amdgcn_mfma_f32_32x32x16_bf16(bf[c], a0[c], acc0, 0, 0, 0); acc1 = __builtin_amdgcn_mfma_f32_32x32x16_bf16(bf[c], a1[c], acc1, 0, 0, 0); }
;     }
.LBB0_1434:
	v_readlane_b32 s16, v251, 49
	s_nop 0
	s_mul_i32 s17, s16, 11
	s_lshl_b32 s22, s16, 14
	s_lshl_b32 s28, s9, 14
	s_and_b32 s29, s2, 64
	s_lshl_b32 s29, s29, 7
	s_add_i32 s28, s28, s29
	s_add_u32 s18, s4, s28
	s_addc_u32 s19, s5, 0
	s_lshl_b32 s28, s8, 14
	s_and_b32 s29, s3, 0x7f
	s_lshl_b32 s29, s29, 7
	s_add_i32 s28, s28, s29
	s_add_u32 s20, s6, s28
	s_addc_u32 s21, s7, 0
	v_and_b32_e32 v169, 31, v200
	v_lshrrev_b32_e32 v170, 5, v200
	v_lshlrev_b32_e32 v170, 4, v170
	v_lshlrev_b32_e32 v164, 4, v200
	v_and_b32_e32 v171, 15, v169
	v_lshrrev_b32_e32 v172, 4, v169
	v_lshlrev_b32_e32 v172, 10, v172
	v_lshl_add_u32 v172, v171, 6, v172
	v_add_u32_e32 v172, v172, v170
	v_add_u32_e32 v172, s22, v172
	v_lshrrev_b32_e32 v173, 3, v171
	v_lshlrev_b32_e32 v173, 5, v173
	v_add_u32_e32 v165, v172, v173
	v_xor_b32_e32 v173, 32, v173
	v_add_u32_e32 v166, v172, v173
	v_bfe_u32 v171, v169, 2, 1
	v_lshrrev_b32_e32 v173, 3, v169
	v_and_b32_e32 v174, 3, v169
	v_lshl_or_b32 v173, v173, 2, v174
	v_lshlrev_b32_e32 v171, 10, v171
	v_lshl_add_u32 v171, v173, 6, v171
	v_add_u32_e32 v171, v171, v170
	v_add_u32_e32 v171, 0x1000, v171
	v_add_u32_e32 v171, s22, v171
	v_lshrrev_b32_e32 v174, 3, v173
	v_lshlrev_b32_e32 v174, 5, v174
	v_add_u32_e32 v167, v171, v174
	v_xor_b32_e32 v174, 32, v174
	v_add_u32_e32 v168, v171, v174
	s_add_i32 s23, s17, 0
	s_lshr_b32 s24, s23, 1
	s_lshl_b32 s24, s24, 14
	s_and_b32 s23, s23, 1
	s_lshl_b32 s23, s23, 10
	s_or_b32 s23, s24, s23
	s_add_u32 s24, s18, s23
	s_addc_u32 s25, s19, 0
	s_add_u32 s26, s20, s23
	s_addc_u32 s27, s21, 0
	s_add_i32 m0, s22, 0
	s_nop 0
	global_load_lds_dwordx4 v164, s[24:25]
	s_add_u32 s24, s24, 0x800
	s_addc_u32 s25, s25, 0
	s_add_i32 m0, s22, 1024
	s_nop 0
	global_load_lds_dwordx4 v164, s[24:25]
	s_add_u32 s24, s24, 0x800
	s_addc_u32 s25, s25, 0
	s_add_i32 m0, s22, 2048
	s_nop 0
	global_load_lds_dwordx4 v164, s[24:25]
	s_add_u32 s24, s24, 0x800
	s_addc_u32 s25, s25, 0
	s_add_i32 m0, s22, 3072
	s_nop 0
	global_load_lds_dwordx4 v164, s[24:25]
	s_add_i32 m0, s22, 4096
	s_nop 0
	global_load_lds_dwordx4 v164, s[26:27]
	s_add_u32 s26, s26, 0x800
	s_addc_u32 s27, s27, 0
	s_add_i32 m0, s22, 5120
	s_nop 0
	global_load_lds_dwordx4 v164, s[26:27]
	s_add_i32 s23, s17, 1
	s_lshr_b32 s24, s23, 1
	s_lshl_b32 s24, s24, 14
	s_and_b32 s23, s23, 1
	s_lshl_b32 s23, s23, 10
	s_or_b32 s23, s24, s23
	s_add_u32 s24, s18, s23
	s_addc_u32 s25, s19, 0
	s_add_u32 s26, s20, s23
	s_addc_u32 s27, s21, 0
	s_add_i32 m0, s22, 6144
	s_nop 0
	global_load_lds_dwordx4 v164, s[24:25]
	s_add_u32 s24, s24, 0x800
	s_addc_u32 s25, s25, 0
	s_add_i32 m0, s22, 7168
	s_nop 0
	global_load_lds_dwordx4 v164, s[24:25]
	s_add_u32 s24, s24, 0x800
	s_addc_u32 s25, s25, 0
	s_add_i32 m0, s22, 8192
	s_nop 0
	global_load_lds_dwordx4 v164, s[24:25]
	s_add_u32 s24, s24, 0x800
	s_addc_u32 s25, s25, 0
	s_add_i32 m0, s22, 9216
	s_nop 0
	global_load_lds_dwordx4 v164, s[24:25]
	s_add_i32 m0, s22, 10240
	s_nop 0
	global_load_lds_dwordx4 v164, s[26:27]
	s_add_u32 s26, s26, 0x800
	s_addc_u32 s27, s27, 0
	s_add_i32 m0, s22, 11264
	s_nop 0
	global_load_lds_dwordx4 v164, s[26:27]
	s_waitcnt vmcnt(6)
	ds_read_b128 v[172:175], v167
	ds_read_b128 v[176:179], v165
	ds_read_b128 v[180:183], v165 offset:2048
	ds_read_b128 v[184:187], v168
	ds_read_b128 v[188:191], v166
	ds_read_b128 v[192:195], v166 offset:2048
	s_waitcnt lgkmcnt(0)
	s_add_i32 s23, s17, 2
	s_lshr_b32 s24, s23, 1
	s_lshl_b32 s24, s24, 14
	s_and_b32 s23, s23, 1
	s_lshl_b32 s23, s23, 10
	s_or_b32 s23, s24, s23
	s_add_u32 s24, s18, s23
	s_addc_u32 s25, s19, 0
	s_add_u32 s26, s20, s23
	s_addc_u32 s27, s21, 0
	s_add_i32 m0, s22, 0
	s_nop 0
	global_load_lds_dwordx4 v164, s[24:25]
	s_add_u32 s24, s24, 0x800
	s_addc_u32 s25, s25, 0
	s_add_i32 m0, s22, 1024
	s_nop 0
	global_load_lds_dwordx4 v164, s[24:25]
	s_add_u32 s24, s24, 0x800
	s_addc_u32 s25, s25, 0
	s_add_i32 m0, s22, 2048
	s_nop 0
	global_load_lds_dwordx4 v164, s[24:25]
	s_add_u32 s24, s24, 0x800
	s_addc_u32 s25, s25, 0
	s_add_i32 m0, s22, 3072
	s_nop 0
	global_load_lds_dwordx4 v164, s[24:25]
	s_add_i32 m0, s22, 4096
	s_nop 0
	global_load_lds_dwordx4 v164, s[26:27]
	s_add_u32 s26, s26, 0x800
	s_addc_u32 s27, s27, 0
	s_add_i32 m0, s22, 5120
	s_nop 0
	global_load_lds_dwordx4 v164, s[26:27]
	v_mfma_f32_32x32x16_bf16 v[0:15], v[172:175], v[176:179], v[0:15]
	v_mfma_f32_32x32x16_bf16 v[16:31], v[172:175], v[180:183], v[16:31]
	v_mfma_f32_32x32x16_bf16 v[0:15], v[184:187], v[188:191], v[0:15]
	v_mfma_f32_32x32x16_bf16 v[16:31], v[184:187], v[192:195], v[16:31]
	s_waitcnt vmcnt(6)
	ds_read_b128 v[172:175], v167 offset:6144
	ds_read_b128 v[176:179], v165 offset:6144
	ds_read_b128 v[180:183], v165 offset:8192
	ds_read_b128 v[184:187], v168 offset:6144
	ds_read_b128 v[188:191], v166 offset:6144
	ds_read_b128 v[192:195], v166 offset:8192
	s_waitcnt lgkmcnt(0)
	s_add_i32 s23, s17, 3
	s_lshr_b32 s24, s23, 1
	s_lshl_b32 s24, s24, 14
	s_and_b32 s23, s23, 1
	s_lshl_b32 s23, s23, 10
	s_or_b32 s23, s24, s23
	s_add_u32 s24, s18, s23
	s_addc_u32 s25, s19, 0
	s_add_u32 s26, s20, s23
	s_addc_u32 s27, s21, 0
	s_add_i32 m0, s22, 6144
	s_nop 0
	global_load_lds_dwordx4 v164, s[24:25]
	s_add_u32 s24, s24, 0x800
	s_addc_u32 s25, s25, 0
	s_add_i32 m0, s22, 7168
	s_nop 0
	global_load_lds_dwordx4 v164, s[24:25]
	s_add_u32 s24, s24, 0x800
	s_addc_u32 s25, s25, 0
	s_add_i32 m0, s22, 8192
	s_nop 0
	global_load_lds_dwordx4 v164, s[24:25]
	s_add_u32 s24, s24, 0x800
	s_addc_u32 s25, s25, 0
	s_add_i32 m0, s22, 9216
	s_nop 0
	global_load_lds_dwordx4 v164, s[24:25]
	s_add_i32 m0, s22, 10240
	s_nop 0
	global_load_lds_dwordx4 v164, s[26:27]
	s_add_u32 s26, s26, 0x800
	s_addc_u32 s27, s27, 0
	s_add_i32 m0, s22, 11264
	s_nop 0
	global_load_lds_dwordx4 v164, s[26:27]
	v_mfma_f32_32x32x16_bf16 v[0:15], v[172:175], v[176:179], v[0:15]
	v_mfma_f32_32x32x16_bf16 v[16:31], v[172:175], v[180:183], v[16:31]
	v_mfma_f32_32x32x16_bf16 v[0:15], v[184:187], v[188:191], v[0:15]
	v_mfma_f32_32x32x16_bf16 v[16:31], v[184:187], v[192:195], v[16:31]
	s_waitcnt vmcnt(6)
; __host__ __device__ __forceinline__ size_t img_off(int row, int col, int nkt) { return ((size_t)((row >> 7) * nkt + (col >> 6)) << 14) + (size_t)lds_byte(row & 127, col & 63); }
; __host__ __device__ __forceinline__ size_t img_off_b(int row, int col, int nkt) { return img_off((row & ~31) | invperm32(row & 31), col, nkt); }
; template <int K, int MODE>
; __device__ __forceinline__ void skinny_tile(Frame& F, const Args& A, const bf16* Am  , const bf16* Bt  ) {
;     ...
; #pragma unroll 1
;     for (int k0 = 0; k0 < NK; k0 += CH) {
;         bf16x8 bf[CH], a0[CH], a1[CH];
; #pragma unroll
;         for (int c = 0; c < CH; ++c) { const int kc = kc0 + 16 * (k0 + c); bf[c] = *(const bf16x8*)(bb + pg8::img_off_b(brow, kc, K / 64)); a0[c] = *(const bf16x8*)(ab + pg8::img_off(arow, kc, K / 64)); a1[c] = *(const bf16x8*)(ab + pg8::img_off(arow + 32, kc, K / 64)); }
; #pragma unroll
;         for (int c = 0; c < CH; ++c) { acc0 = __builtin_amdgcn_mfma_f32_32x32x16_bf16(bf[c], a0[c], acc0, 0, 0, 0); acc1 = __builtin_amdgcn_mfma_f32_32x32x16_bf16(bf[c], a1[c], acc1, 0, 0, 0); }
;     }
	ds_read_b128 v[172:175], v167
	ds_read_b128 v[176:179], v165
	ds_read_b128 v[180:183], v165 offset:2048
	ds_read_b128 v[184:187], v168
	ds_read_b128 v[188:191], v166
	ds_read_b128 v[192:195], v166 offset:2048
	s_waitcnt lgkmcnt(0)
	s_add_i32 s23, s17, 4
	s_lshr_b32 s24, s23, 1
	s_lshl_b32 s24, s24, 14
	s_and_b32 s23, s23, 1
	s_lshl_b32 s23, s23, 10
	s_or_b32 s23, s24, s23
	s_add_u32 s24, s18, s23
	s_addc_u32 s25, s19, 0
	s_add_u32 s26, s20, s23
	s_addc_u32 s27, s21, 0
	s_add_i32 m0, s22, 0
	s_nop 0
	global_load_lds_dwordx4 v164, s[24:25]
	s_add_u32 s24, s24, 0x800
	s_addc_u32 s25, s25, 0
	s_add_i32 m0, s22, 1024
	s_nop 0
	global_load_lds_dwordx4 v164, s[24:25]
	s_add_u32 s24, s24, 0x800
	s_addc_u32 s25, s25, 0
	s_add_i32 m0, s22, 2048
	s_nop 0
	global_load_lds_dwordx4 v164, s[24:25]
	s_add_u32 s24, s24, 0x800
	s_addc_u32 s25, s25, 0
	s_add_i32 m0, s22, 3072
	s_nop 0
	global_load_lds_dwordx4 v164, s[24:25]
	s_add_i32 m0, s22, 4096
	s_nop 0
	global_load_lds_dwordx4 v164, s[26:27]
	s_add_u32 s26, s26, 0x800
	s_addc_u32 s27, s27, 0
	s_add_i32 m0, s22, 5120
	s_nop 0
	global_load_lds_dwordx4 v164, s[26:27]
	v_mfma_f32_32x32x16_bf16 v[0:15], v[172:175], v[176:179], v[0:15]
	v_mfma_f32_32x32x16_bf16 v[16:31], v[172:175], v[180:183], v[16:31]
	v_mfma_f32_32x32x16_bf16 v[0:15], v[184:187], v[188:191], v[0:15]
	v_mfma_f32_32x32x16_bf16 v[16:31], v[184:187], v[192:195], v[16:31]
	s_waitcnt vmcnt(6)
	ds_read_b128 v[172:175], v167 offset:6144
	ds_read_b128 v[176:179], v165 offset:6144
	ds_read_b128 v[180:183], v165 offset:8192
	ds_read_b128 v[184:187], v168 offset:6144
	ds_read_b128 v[188:191], v166 offset:6144
	ds_read_b128 v[192:195], v166 offset:8192
	s_waitcnt lgkmcnt(0)
	s_add_i32 s23, s17, 5
	s_lshr_b32 s24, s23, 1
	s_lshl_b32 s24, s24, 14
	s_and_b32 s23, s23, 1
	s_lshl_b32 s23, s23, 10
	s_or_b32 s23, s24, s23
	s_add_u32 s24, s18, s23
	s_addc_u32 s25, s19, 0
	s_add_u32 s26, s20, s23
	s_addc_u32 s27, s21, 0
	s_add_i32 m0, s22, 6144
	s_nop 0
	global_load_lds_dwordx4 v164, s[24:25]
	s_add_u32 s24, s24, 0x800
	s_addc_u32 s25, s25, 0
	s_add_i32 m0, s22, 7168
	s_nop 0
	global_load_lds_dwordx4 v164, s[24:25]
	s_add_u32 s24, s24, 0x800
	s_addc_u32 s25, s25, 0
	s_add_i32 m0, s22, 8192
	s_nop 0
	global_load_lds_dwordx4 v164, s[24:25]
	s_add_u32 s24, s24, 0x800
	s_addc_u32 s25, s25, 0
	s_add_i32 m0, s22, 9216
	s_nop 0
	global_load_lds_dwordx4 v164, s[24:25]
	s_add_i32 m0, s22, 10240
	s_nop 0
	global_load_lds_dwordx4 v164, s[26:27]
	s_add_u32 s26, s26, 0x800
	s_addc_u32 s27, s27, 0
	s_add_i32 m0, s22, 11264
	s_nop 0
	global_load_lds_dwordx4 v164, s[26:27]
	v_mfma_f32_32x32x16_bf16 v[0:15], v[172:175], v[176:179], v[0:15]
	v_mfma_f32_32x32x16_bf16 v[16:31], v[172:175], v[180:183], v[16:31]
	v_mfma_f32_32x32x16_bf16 v[0:15], v[184:187], v[188:191], v[0:15]
	v_mfma_f32_32x32x16_bf16 v[16:31], v[184:187], v[192:195], v[16:31]
	s_waitcnt vmcnt(6)
	ds_read_b128 v[172:175], v167
	ds_read_b128 v[176:179], v165
	ds_read_b128 v[180:183], v165 offset:2048
	ds_read_b128 v[184:187], v168
	ds_read_b128 v[188:191], v166
	ds_read_b128 v[192:195], v166 offset:2048
	s_waitcnt lgkmcnt(0)
	s_add_i32 s23, s17, 6
	s_lshr_b32 s24, s23, 1
	s_lshl_b32 s24, s24, 14
	s_and_b32 s23, s23, 1
	s_lshl_b32 s23, s23, 10
	s_or_b32 s23, s24, s23
	s_add_u32 s24, s18, s23
	s_addc_u32 s25, s19, 0
	s_add_u32 s26, s20, s23
	s_addc_u32 s27, s21, 0
	s_add_i32 m0, s22, 0
	s_nop 0
	global_load_lds_dwordx4 v164, s[24:25]
	s_add_u32 s24, s24, 0x800
	s_addc_u32 s25, s25, 0
	s_add_i32 m0, s22, 1024
	s_nop 0
	global_load_lds_dwordx4 v164, s[24:25]
	s_add_u32 s24, s24, 0x800
	s_addc_u32 s25, s25, 0
	s_add_i32 m0, s22, 2048
	s_nop 0
	global_load_lds_dwordx4 v164, s[24:25]
	s_add_u32 s24, s24, 0x800
	s_addc_u32 s25, s25, 0
	s_add_i32 m0, s22, 3072
	s_nop 0
	global_load_lds_dwordx4 v164, s[24:25]
	s_add_i32 m0, s22, 4096
	s_nop 0
	global_load_lds_dwordx4 v164, s[26:27]
	s_add_u32 s26, s26, 0x800
	s_addc_u32 s27, s27, 0
	s_add_i32 m0, s22, 5120
	s_nop 0
	global_load_lds_dwordx4 v164, s[26:27]
	v_mfma_f32_32x32x16_bf16 v[0:15], v[172:175], v[176:179], v[0:15]
	v_mfma_f32_32x32x16_bf16 v[16:31], v[172:175], v[180:183], v[16:31]
	v_mfma_f32_32x32x16_bf16 v[0:15], v[184:187], v[188:191], v[0:15]
	v_mfma_f32_32x32x16_bf16 v[16:31], v[184:187], v[192:195], v[16:31]
	s_waitcnt vmcnt(6)
	ds_read_b128 v[172:175], v167 offset:6144
	ds_read_b128 v[176:179], v165 offset:6144
	ds_read_b128 v[180:183], v165 offset:8192
	ds_read_b128 v[184:187], v168 offset:6144
	ds_read_b128 v[188:191], v166 offset:6144
	ds_read_b128 v[192:195], v166 offset:8192
	s_waitcnt lgkmcnt(0)
	s_add_i32 s23, s17, 7
	s_lshr_b32 s24, s23, 1
	s_lshl_b32 s24, s24, 14
	s_and_b32 s23, s23, 1
	s_lshl_b32 s23, s23, 10
	s_or_b32 s23, s24, s23
	s_add_u32 s24, s18, s23
	s_addc_u32 s25, s19, 0
	s_add_u32 s26, s20, s23
	s_addc_u32 s27, s21, 0
	s_add_i32 m0, s22, 6144
	s_nop 0
	global_load_lds_dwordx4 v164, s[24:25]
	s_add_u32 s24, s24, 0x800
	s_addc_u32 s25, s25, 0
	s_add_i32 m0, s22, 7168
	s_nop 0
	global_load_lds_dwordx4 v164, s[24:25]
	s_add_u32 s24, s24, 0x800
	s_addc_u32 s25, s25, 0
	s_add_i32 m0, s22, 8192
	s_nop 0
	global_load_lds_dwordx4 v164, s[24:25]
	s_add_u32 s24, s24, 0x800
	s_addc_u32 s25, s25, 0
	s_add_i32 m0, s22, 9216
	s_nop 0
	global_load_lds_dwordx4 v164, s[24:25]
	s_add_i32 m0, s22, 10240
	s_nop 0
	global_load_lds_dwordx4 v164, s[26:27]
	s_add_u32 s26, s26, 0x800
	s_addc_u32 s27, s27, 0
	s_add_i32 m0, s22, 11264
	s_nop 0
	global_load_lds_dwordx4 v164, s[26:27]
	v_mfma_f32_32x32x16_bf16 v[0:15], v[172:175], v[176:179], v[0:15]
	v_mfma_f32_32x32x16_bf16 v[16:31], v[172:175], v[180:183], v[16:31]
	v_mfma_f32_32x32x16_bf16 v[0:15], v[184:187], v[188:191], v[0:15]
	v_mfma_f32_32x32x16_bf16 v[16:31], v[184:187], v[192:195], v[16:31]
	s_waitcnt vmcnt(6)
; __host__ __device__ __forceinline__ size_t img_off(int row, int col, int nkt) { return ((size_t)((row >> 7) * nkt + (col >> 6)) << 14) + (size_t)lds_byte(row & 127, col & 63); }
; __host__ __device__ __forceinline__ size_t img_off_b(int row, int col, int nkt) { return img_off((row & ~31) | invperm32(row & 31), col, nkt); }
; #define LAS __attribute__((address_space(3)))
; template <int K, int MODE>
; __device__ __forceinline__ void skinny_tile(Frame& F, const Args& A, const bf16* Am  , const bf16* Bt  ) {
;     ...
; #pragma unroll 1
;     for (int k0 = 0; k0 < NK; k0 += CH) {
;         bf16x8 bf[CH], a0[CH], a1[CH];
; #pragma unroll
;         for (int c = 0; c < CH; ++c) { const int kc = kc0 + 16 * (k0 + c); bf[c] = *(const bf16x8*)(bb + pg8::img_off_b(brow, kc, K / 64)); a0[c] = *(const bf16x8*)(ab + pg8::img_off(arow, kc, K / 64)); a1[c] = *(const bf16x8*)(ab + pg8::img_off(arow + 32, kc, K / 64)); }
; #pragma unroll
;         for (int c = 0; c < CH; ++c) { acc0 = __builtin_amdgcn_mfma_f32_32x32x16_bf16(bf[c], a0[c], acc0, 0, 0, 0); acc1 = __builtin_amdgcn_mfma_f32_32x32x16_bf16(bf[c], a1[c], acc1, 0, 0, 0); }
;     }
;     LAS float* red = (LAS float*)(F.lds + RING_OFF);
; #pragma unroll
;     for (int q = 0; q < 16; ++q) { red[((w * 2 + 0) * 16 + q) * 64 + lane] = acc0[q]; red[((w * 2 + 1) * 16 + q) * 64 + lane] = acc1[q]; }
	ds_read_b128 v[172:175], v167
	ds_read_b128 v[176:179], v165
	ds_read_b128 v[180:183], v165 offset:2048
	ds_read_b128 v[184:187], v168
	ds_read_b128 v[188:191], v166
	ds_read_b128 v[192:195], v166 offset:2048
	s_waitcnt lgkmcnt(0)
	s_add_i32 s23, s17, 8
	s_lshr_b32 s24, s23, 1
	s_lshl_b32 s24, s24, 14
	s_and_b32 s23, s23, 1
	s_lshl_b32 s23, s23, 10
	s_or_b32 s23, s24, s23
	s_add_u32 s24, s18, s23
	s_addc_u32 s25, s19, 0
	s_add_u32 s26, s20, s23
	s_addc_u32 s27, s21, 0
	s_add_i32 m0, s22, 0
	s_nop 0
	global_load_lds_dwordx4 v164, s[24:25]
	s_add_u32 s24, s24, 0x800
	s_addc_u32 s25, s25, 0
	s_add_i32 m0, s22, 1024
	s_nop 0
	global_load_lds_dwordx4 v164, s[24:25]
	s_add_u32 s24, s24, 0x800
	s_addc_u32 s25, s25, 0
	s_add_i32 m0, s22, 2048
	s_nop 0
	global_load_lds_dwordx4 v164, s[24:25]
	s_add_u32 s24, s24, 0x800
	s_addc_u32 s25, s25, 0
	s_add_i32 m0, s22, 3072
	s_nop 0
	global_load_lds_dwordx4 v164, s[24:25]
	s_add_i32 m0, s22, 4096
	s_nop 0
	global_load_lds_dwordx4 v164, s[26:27]
	s_add_u32 s26, s26, 0x800
	s_addc_u32 s27, s27, 0
	s_add_i32 m0, s22, 5120
	s_nop 0
	global_load_lds_dwordx4 v164, s[26:27]
	v_mfma_f32_32x32x16_bf16 v[0:15], v[172:175], v[176:179], v[0:15]
	v_mfma_f32_32x32x16_bf16 v[16:31], v[172:175], v[180:183], v[16:31]
	v_mfma_f32_32x32x16_bf16 v[0:15], v[184:187], v[188:191], v[0:15]
	v_mfma_f32_32x32x16_bf16 v[16:31], v[184:187], v[192:195], v[16:31]
	s_waitcnt vmcnt(6)
	ds_read_b128 v[172:175], v167 offset:6144
	ds_read_b128 v[176:179], v165 offset:6144
	ds_read_b128 v[180:183], v165 offset:8192
	ds_read_b128 v[184:187], v168 offset:6144
	ds_read_b128 v[188:191], v166 offset:6144
	ds_read_b128 v[192:195], v166 offset:8192
	s_waitcnt lgkmcnt(0)
	s_add_i32 s23, s17, 9
	s_lshr_b32 s24, s23, 1
	s_lshl_b32 s24, s24, 14
	s_and_b32 s23, s23, 1
	s_lshl_b32 s23, s23, 10
	s_or_b32 s23, s24, s23
	s_add_u32 s24, s18, s23
	s_addc_u32 s25, s19, 0
	s_add_u32 s26, s20, s23
	s_addc_u32 s27, s21, 0
	s_add_i32 m0, s22, 6144
	s_nop 0
	global_load_lds_dwordx4 v164, s[24:25]
	s_add_u32 s24, s24, 0x800
	s_addc_u32 s25, s25, 0
	s_add_i32 m0, s22, 7168
	s_nop 0
	global_load_lds_dwordx4 v164, s[24:25]
	s_add_u32 s24, s24, 0x800
	s_addc_u32 s25, s25, 0
	s_add_i32 m0, s22, 8192
	s_nop 0
	global_load_lds_dwordx4 v164, s[24:25]
	s_add_u32 s24, s24, 0x800
	s_addc_u32 s25, s25, 0
	s_add_i32 m0, s22, 9216
	s_nop 0
	global_load_lds_dwordx4 v164, s[24:25]
	s_add_i32 m0, s22, 10240
	s_nop 0
	global_load_lds_dwordx4 v164, s[26:27]
	s_add_u32 s26, s26, 0x800
	s_addc_u32 s27, s27, 0
	s_add_i32 m0, s22, 11264
	s_nop 0
	global_load_lds_dwordx4 v164, s[26:27]
	v_mfma_f32_32x32x16_bf16 v[0:15], v[172:175], v[176:179], v[0:15]
	v_mfma_f32_32x32x16_bf16 v[16:31], v[172:175], v[180:183], v[16:31]
	v_mfma_f32_32x32x16_bf16 v[0:15], v[184:187], v[188:191], v[0:15]
	v_mfma_f32_32x32x16_bf16 v[16:31], v[184:187], v[192:195], v[16:31]
	s_waitcnt vmcnt(6)
	ds_read_b128 v[172:175], v167
	ds_read_b128 v[176:179], v165
	ds_read_b128 v[180:183], v165 offset:2048
	ds_read_b128 v[184:187], v168
	ds_read_b128 v[188:191], v166
	ds_read_b128 v[192:195], v166 offset:2048
	s_waitcnt lgkmcnt(0)
	s_add_i32 s23, s17, 10
	s_lshr_b32 s24, s23, 1
	s_lshl_b32 s24, s24, 14
	s_and_b32 s23, s23, 1
	s_lshl_b32 s23, s23, 10
	s_or_b32 s23, s24, s23
	s_add_u32 s24, s18, s23
	s_addc_u32 s25, s19, 0
	s_add_u32 s26, s20, s23
	s_addc_u32 s27, s21, 0
	s_add_i32 m0, s22, 0
	s_nop 0
	global_load_lds_dwordx4 v164, s[24:25]
	s_add_u32 s24, s24, 0x800
	s_addc_u32 s25, s25, 0
	s_add_i32 m0, s22, 1024
	s_nop 0
	global_load_lds_dwordx4 v164, s[24:25]
	s_add_u32 s24, s24, 0x800
	s_addc_u32 s25, s25, 0
	s_add_i32 m0, s22, 2048
	s_nop 0
	global_load_lds_dwordx4 v164, s[24:25]
	s_add_u32 s24, s24, 0x800
	s_addc_u32 s25, s25, 0
	s_add_i32 m0, s22, 3072
	s_nop 0
	global_load_lds_dwordx4 v164, s[24:25]
	s_add_i32 m0, s22, 4096
	s_nop 0
	global_load_lds_dwordx4 v164, s[26:27]
	s_add_u32 s26, s26, 0x800
	s_addc_u32 s27, s27, 0
	s_add_i32 m0, s22, 5120
	s_nop 0
	global_load_lds_dwordx4 v164, s[26:27]
	v_mfma_f32_32x32x16_bf16 v[0:15], v[172:175], v[176:179], v[0:15]
	v_mfma_f32_32x32x16_bf16 v[16:31], v[172:175], v[180:183], v[16:31]
	v_mfma_f32_32x32x16_bf16 v[0:15], v[184:187], v[188:191], v[0:15]
	v_mfma_f32_32x32x16_bf16 v[16:31], v[184:187], v[192:195], v[16:31]
	s_waitcnt vmcnt(6)
	ds_read_b128 v[172:175], v167 offset:6144
	ds_read_b128 v[176:179], v165 offset:6144
	ds_read_b128 v[180:183], v165 offset:8192
	ds_read_b128 v[184:187], v168 offset:6144
	ds_read_b128 v[188:191], v166 offset:6144
	ds_read_b128 v[192:195], v166 offset:8192
	s_waitcnt lgkmcnt(0)
	v_mfma_f32_32x32x16_bf16 v[0:15], v[172:175], v[176:179], v[0:15]
	v_mfma_f32_32x32x16_bf16 v[16:31], v[172:175], v[180:183], v[16:31]
	v_mfma_f32_32x32x16_bf16 v[0:15], v[184:187], v[188:191], v[0:15]
	v_mfma_f32_32x32x16_bf16 v[16:31], v[184:187], v[192:195], v[16:31]
	s_waitcnt vmcnt(0)
	ds_read_b128 v[172:175], v167
	ds_read_b128 v[176:179], v165
	ds_read_b128 v[180:183], v165 offset:2048
	ds_read_b128 v[184:187], v168
	ds_read_b128 v[188:191], v166
	ds_read_b128 v[192:195], v166 offset:2048
	s_waitcnt lgkmcnt(0)
	v_mfma_f32_32x32x16_bf16 v[0:15], v[172:175], v[176:179], v[0:15]
	v_mfma_f32_32x32x16_bf16 v[16:31], v[172:175], v[180:183], v[16:31]
	v_mfma_f32_32x32x16_bf16 v[0:15], v[184:187], v[188:191], v[0:15]
	s_nop 1
	v_mfma_f32_32x32x16_bf16 v[16:31], v[184:187], v[192:195], v[16:31]
	s_barrier
; __host__ __device__ __forceinline__ size_t img_off(int row, int col, int nkt) { return ((size_t)((row >> 7) * nkt + (col >> 6)) << 14) + (size_t)lds_byte(row & 127, col & 63); }
; #define LAS __attribute__((address_space(3)))
; __device__ __forceinline__ unsigned pk2(float lo, float hi) { return pg8::cvt_pk_bf16(lo, hi); }
; template <int K, int MODE>
; __device__ __forceinline__ void skinny_tile(Frame& F, const Args& A, const bf16* Am  , const bf16* Bt  ) {
;     ...
;     LAS float* red = (LAS float*)(F.lds + RING_OFF);
; #pragma unroll
;     for (int q = 0; q < 16; ++q) { red[((w * 2 + 0) * 16 + q) * 64 + lane] = acc0[q]; red[((w * 2 + 1) * 16 + q) * 64 + lane] = acc1[q]; }
;     __syncthreads();
;     const int rb = w >> 2, qg = w & 3;
;     f32x4 v = (f32x4){0.f, 0.f, 0.f, 0.f};
; #pragma unroll
;     for (int ww = 0; ww < 8; ++ww)
; #pragma unroll
;         for (int j = 0; j < 4; ++j) v[j] += red[((ww * 2 + rb) * 16 + 4 * qg + j) * 64 + lane];
;     const int srow = r0 + 32 * rb + il, col = c0 + 8 * qg + 4 * hi;
;     float* yp = F.out + O_Y + (size_t)(MP + srow) * DM + col;
;     if (MODE == 0) {
;         const f32x4 x = *(const f32x4*)(A.in[1] + (size_t)srow * DM + col); v = v + x;
;         v2u o; o.x = pk2(v[0], v[1]); o.y = pk2(v[2], v[3]); *(v2u*)((char*)(F.ws + WS_X1B) + pg8::img_off(MP + srow, col, DM / 64)) = o;
;         float s = (v[0] * v[0] + v[1] * v[1]) + (v[2] * v[2] + v[3] * v[3]); s += __shfl_xor(s, 32);
;         if (hi == 0) atomicAdd((float*)F.ws + CW_SS + MP + srow, s);
;     } else {
;         const v2u xb = *(const v2u*)((const char*)(F.ws + WS_X1B) + pg8::img_off(MP + srow, col, DM / 64)); *(f32x4*)yp = v + (f32x4){bf_lo(xb.x), bf_hi(xb.x), bf_lo(xb.y), bf_hi(xb.y)};
;     }
;     __syncthreads();
;     }
	s_nop 7
	ds_write2st64_b32 v40, v0, v1 offset1:1
	s_nop 1
	ds_write2st64_b32 v40, v16, v17 offset0:16 offset1:17
	ds_write2st64_b32 v40, v2, v3 offset0:2 offset1:3
	ds_write2st64_b32 v40, v18, v19 offset0:18 offset1:19
	ds_write2st64_b32 v40, v4, v5 offset0:4 offset1:5
	ds_write2st64_b32 v40, v20, v21 offset0:20 offset1:21
	ds_write2st64_b32 v40, v6, v7 offset0:6 offset1:7
	ds_write2st64_b32 v40, v22, v23 offset0:22 offset1:23
	ds_write2st64_b32 v40, v8, v9 offset0:8 offset1:9
	ds_write2st64_b32 v40, v24, v25 offset0:24 offset1:25
	ds_write2st64_b32 v40, v10, v11 offset0:10 offset1:11
	ds_write2st64_b32 v40, v26, v27 offset0:26 offset1:27
	ds_write2st64_b32 v40, v12, v13 offset0:12 offset1:13
	ds_write2st64_b32 v40, v28, v29 offset0:28 offset1:29
	ds_write2st64_b32 v40, v14, v15 offset0:14 offset1:15
	ds_write2st64_b32 v40, v30, v31 offset0:30 offset1:31
	v_add_u32_e32 v1, s2, v38
	v_add_u32_e32 v2, 0x4000, v1
	v_add_u32_e32 v0, s3, v39
	v_ashrrev_i32_e32 v3, 3, v2
	v_and_b32_e32 v3, -16, v3
	v_ashrrev_i32_e32 v4, 6, v0
	v_lshrrev_b32_e32 v1, 3, v1
	v_add_u32_e32 v4, v3, v4
	v_and_b32_e32 v1, 14, v1
	v_lshrrev_b32_e32 v3, 5, v0
	v_and_or_b32 v1, v3, 1, v1
	v_lshlrev_b32_e32 v3, 6, v2
	v_and_b32_e32 v3, 0x3c0, v3
	v_lshlrev_b32_e32 v6, 1, v0
	v_ashrrev_i32_e32 v5, 31, v4
	v_and_or_b32 v3, v6, 56, v3
	v_lshlrev_b32_e32 v6, 2, v2
	v_lshlrev_b64 v[4:5], 14, v[4:5]
	v_lshlrev_b32_e32 v1, 10, v1
	v_and_b32_e32 v6, 32, v6
	v_bitop3_b32 v32, v3, v1, v6 bitop3:0xde
	v_lshl_add_u64 v[4:5], s[0:1], 0, v[4:5]
	v_lshl_add_u64 v[4:5], v[4:5], 0, v[32:33]
	s_waitcnt lgkmcnt(0)
	s_barrier
	global_load_dwordx2 v[4:5], v[4:5], off
	v_ashrrev_i32_e32 v3, 31, v2
	v_readlane_b32 s8, v251, 6
	ds_read2st64_b32 v[6:7], v45 offset1:1
	ds_read2st64_b32 v[8:9], v45 offset0:2 offset1:3
	ds_read2st64_b32 v[10:11], v45 offset0:32 offset1:33
	ds_read2st64_b32 v[12:13], v45 offset0:34 offset1:35
	ds_read2st64_b32 v[14:15], v45 offset0:64 offset1:65
	ds_read2st64_b32 v[16:17], v45 offset0:66 offset1:67
	ds_read2st64_b32 v[18:19], v45 offset0:96 offset1:97
	ds_read2st64_b32 v[20:21], v45 offset0:98 offset1:99
	ds_read2st64_b32 v[22:23], v45 offset0:128 offset1:129
	ds_read2st64_b32 v[24:25], v45 offset0:130 offset1:131
	ds_read2st64_b32 v[26:27], v45 offset0:160 offset1:161
	ds_read2st64_b32 v[28:29], v45 offset0:162 offset1:163
	ds_read2st64_b32 v[30:31], v45 offset0:192 offset1:193
	ds_read2st64_b32 v[46:47], v45 offset0:194 offset1:195
	ds_read2st64_b32 v[48:49], v45 offset0:224 offset1:225
	ds_read2st64_b32 v[50:51], v45 offset0:226 offset1:227
	v_lshlrev_b64 v[2:3], 12, v[2:3]
	v_readlane_b32 s14, v251, 12
	v_readlane_b32 s15, v251, 13
	v_ashrrev_i32_e32 v1, 31, v0
	s_waitcnt lgkmcnt(14)
	v_pk_add_f32 v[8:9], v[8:9], 0 op_sel_hi:[1,0]
	v_lshl_add_u64 v[2:3], s[14:15], 0, v[2:3]
	v_pk_add_f32 v[6:7], v[6:7], 0 op_sel_hi:[1,0]
	v_lshl_add_u64 v[52:53], v[0:1], 2, v[2:3]
	s_waitcnt lgkmcnt(13)
	v_pk_add_f32 v[0:1], v[6:7], v[10:11]
	s_waitcnt lgkmcnt(12)
	v_pk_add_f32 v[2:3], v[8:9], v[12:13]
	s_waitcnt lgkmcnt(11)
	v_pk_add_f32 v[0:1], v[0:1], v[14:15]
	s_waitcnt lgkmcnt(10)
	v_pk_add_f32 v[2:3], v[2:3], v[16:17]
	s_waitcnt lgkmcnt(9)
	v_pk_add_f32 v[0:1], v[0:1], v[18:19]
	s_waitcnt lgkmcnt(8)
	v_pk_add_f32 v[2:3], v[2:3], v[20:21]
	s_waitcnt lgkmcnt(7)
	v_pk_add_f32 v[0:1], v[0:1], v[22:23]
	s_waitcnt lgkmcnt(6)
	v_pk_add_f32 v[2:3], v[2:3], v[24:25]
	s_waitcnt lgkmcnt(5)
	v_pk_add_f32 v[0:1], v[0:1], v[26:27]
	s_waitcnt lgkmcnt(4)
	v_pk_add_f32 v[2:3], v[2:3], v[28:29]
	v_readlane_b32 s2, v251, 3
	s_waitcnt lgkmcnt(2)
	v_pk_add_f32 v[2:3], v[2:3], v[46:47]
	v_pk_add_f32 v[0:1], v[0:1], v[30:31]
	s_add_i32 s96, s96, s2
	s_waitcnt lgkmcnt(1)
	v_pk_add_f32 v[0:1], v[0:1], v[48:49]
	s_waitcnt lgkmcnt(0)
	v_pk_add_f32 v[2:3], v[2:3], v[50:51]
	s_cmpk_gt_i32 s96, 0xff
	v_readlane_b32 s9, v251, 7
	v_readlane_b32 s10, v251, 8
	v_readlane_b32 s11, v251, 9
	v_readlane_b32 s12, v251, 10
	v_readlane_b32 s13, v251, 11
	s_waitcnt vmcnt(0)
	v_lshlrev_b32_e32 v6, 16, v4
	v_and_b32_e32 v7, 0xffff0000, v4
	v_lshlrev_b32_e32 v4, 16, v5
	v_and_b32_e32 v5, 0xffff0000, v5
	v_pk_add_f32 v[2:3], v[2:3], v[4:5]
	v_pk_add_f32 v[0:1], v[0:1], v[6:7]
	global_store_dwordx4 v[52:53], v[0:3], off
	s_barrier
	s_cbranch_scc0 .LBB0_1433
